# GEMM tile loops: next tile's (pm,pn) in closed form (13 SALU) instead of the generic StaticOrder division chain; original kept as the grid!=256 path
# baseline (speedup 1.0000x reference)
.LBB0_149:
	s_add_i32 s93, s9, 1
	s_mul_i32 s6, s93, s73
	s_mul_hi_u32 s7, s93, s72
	s_add_i32 s7, s7, s6
	s_mul_i32 s6, s93, s72
	s_add_u32 s38, s6, s2
	s_addc_u32 s39, s7, s3
	v_cmp_gt_i64_e32 vcc, s[38:39], v[162:163]
	v_cmp_lt_i64_e64 s[6:7], s[38:39], v[160:161]
	s_cbranch_vccnz .LBB0_151
	s_cmp_eq_u32 s66, 0x100
	s_cbranch_scc0 .Ltix_orig_0
	s_lshr_b32 s98, s38, 3
	s_and_b32 s99, s38, 7
	s_lshl_b32 s99, s99, 4
	s_and_b32 s36, s98, 7
	s_add_i32 s36, s36, s99
	s_cmp_ge_u32 s98, 56
	s_cselect_b32 s99, 8, 0
	s_cselect_b32 s34, 56, 0
	s_add_i32 s36, s36, s99
	s_sub_i32 s34, s98, s34
	s_lshr_b32 s34, s34, 3
	s_branch .LBB0_151
.Ltix_orig_0:
	s_ashr_i32 s11, s38, 31
	s_lshr_b32 s11, s11, 29
	s_add_i32 s11, s38, s11
	s_ashr_i32 s22, s11, 3
	s_and_b32 s11, s11, -8
	s_sub_i32 s11, s38, s11
	s_cmp_lt_i32 s11, 0
	s_movk_i32 s34, 0x71
	s_cselect_b32 s34, s34, 0x70
	s_mul_i32 s11, s34, s11
	s_add_i32 s11, s11, s22
	s_mul_hi_i32 s22, s11, 0x92492493
	s_add_i32 s22, s22, s11
	s_lshr_b32 s34, s22, 31
	s_ashr_i32 s22, s22, 5
	s_add_i32 s22, s22, s34
	s_lshl_b32 s35, s22, 3
	s_sub_i32 s34, 0x80, s35
	s_min_i32 s36, s34, 8
	s_abs_i32 s34, s36
	v_cvt_f32_u32_e32 v0, s34
	s_sub_i32 s38, 0, s34
	s_mul_i32 s22, s22, 56
	s_sub_i32 s11, s11, s22
	v_rcp_iflag_f32_e32 v0, v0
	s_abs_i32 s22, s11
	s_xor_b32 s37, s11, s36
	s_ashr_i32 s37, s37, 31
	v_mul_f32_e32 v0, 0x4f7ffffe, v0
	v_cvt_u32_f32_e32 v0, v0
	s_nop 0
	v_readfirstlane_b32 s39, v0
	s_mul_i32 s38, s38, s39
	s_mul_hi_u32 s38, s39, s38
	s_add_i32 s39, s39, s38
	s_mul_hi_u32 s38, s22, s39
	s_mul_i32 s39, s38, s34
	s_sub_i32 s22, s22, s39
	s_add_i32 s40, s38, 1
	s_sub_i32 s39, s22, s34
	s_cmp_ge_u32 s22, s34
	s_cselect_b32 s38, s40, s38
	s_cselect_b32 s22, s39, s22
	s_add_i32 s39, s38, 1
	s_cmp_ge_u32 s22, s34
	s_cselect_b32 s22, s39, s38
	s_xor_b32 s22, s22, s37
	s_sub_i32 s34, s22, s37
	s_mul_i32 s22, s34, s36
	s_sub_i32 s11, s11, s22
	s_add_i32 s36, s11, s35

.LBB0_610:
	s_add_i32 s43, s43, 1
	s_mul_i32 s4, s43, s73
	s_mul_hi_u32 s5, s43, s72
	s_add_i32 s5, s5, s4
	s_mul_i32 s4, s43, s72
	s_add_u32 s18, s4, s2
	s_addc_u32 s19, s5, s3
	v_cmp_gt_i64_e32 vcc, s[18:19], v[142:143]
	v_cmp_lt_i64_e64 s[4:5], s[18:19], v[140:141]
	s_cbranch_vccnz .LBB0_616
	s_cmp_eq_u32 s66, 0x100
	s_cbranch_scc0 .Ltix_orig_1
	s_lshr_b32 s98, s18, 3
	s_and_b32 s99, s18, 7
	s_lshl_b32 s99, s99, 4
	s_and_b32 s16, s98, 7
	s_add_i32 s16, s16, s99
	s_cmp_ge_u32 s98, 32
	s_cselect_b32 s99, 8, 0
	s_cselect_b32 s14, 32, 0
	s_add_i32 s16, s16, s99
	s_sub_i32 s14, s98, s14
	s_lshr_b32 s14, s14, 3
	s_branch .LBB0_616
.Ltix_orig_1:
	s_ashr_i32 s14, s18, 31
	s_lshr_b32 s14, s14, 29
	s_add_i32 s16, s18, s14
	s_and_b32 s14, s16, -8
	s_sub_i32 s17, s18, s14
	s_cmp_gt_i32 s17, -1
	s_mov_b64 s[14:15], -1
	s_cbranch_scc0 .LBB0_613
	s_lshl_b32 s18, s17, 6
	s_mov_b64 s[14:15], 0

.LBB0_702:
	s_add_i32 s39, s40, 1
	s_mul_i32 s0, s39, s73
	s_mul_hi_u32 s1, s39, s72
	s_add_i32 s1, s1, s0
	s_mul_i32 s0, s39, s72
	s_add_u32 s14, s0, s2
	s_addc_u32 s15, s1, s3
	v_cmp_gt_i64_e32 vcc, s[14:15], v[142:143]
	v_cmp_lt_i64_e64 s[0:1], s[14:15], v[140:141]
	s_cbranch_vccnz .LBB0_704
	s_cmp_eq_u32 s66, 0x100
	s_cbranch_scc0 .Ltix_orig_2
	s_lshr_b32 s98, s14, 3
	s_and_b32 s99, s14, 7
	s_lshl_b32 s99, s99, 4
	s_and_b32 s12, s98, 7
	s_add_i32 s12, s12, s99
	s_cmp_ge_u32 s98, 176
	s_cselect_b32 s99, 8, 0
	s_cselect_b32 s10, 176, 0
	s_add_i32 s12, s12, s99
	s_sub_i32 s10, s98, s10
	s_lshr_b32 s10, s10, 3
	s_branch .LBB0_704
.Ltix_orig_2:
	s_ashr_i32 s10, s14, 31
	s_lshr_b32 s10, s10, 29
	s_add_i32 s10, s14, s10
	s_ashr_i32 s11, s10, 3
	s_and_b32 s10, s10, -8
	s_sub_i32 s10, s14, s10
	s_cmp_lt_i32 s10, 0
	s_cselect_b32 s12, s29, 0x160
	s_mul_i32 s10, s12, s10
	s_add_i32 s10, s10, s11
	s_mul_hi_i32 s11, s10, 0x2e8ba2e9
	s_lshr_b32 s12, s11, 31
	s_ashr_i32 s11, s11, 5
	s_add_i32 s11, s11, s12
	s_lshl_b32 s12, s11, 3
	s_sub_i32 s13, 0x80, s12
	s_min_i32 s13, s13, 8
	s_abs_i32 s14, s13
	v_cvt_f32_u32_e32 v0, s14
	s_sub_i32 s16, 0, s14
	s_mulk_i32 s11, 0xb0
	s_sub_i32 s11, s10, s11
	v_rcp_iflag_f32_e32 v0, v0
	s_abs_i32 s10, s11
	s_xor_b32 s15, s11, s13
	s_ashr_i32 s15, s15, 31
	v_mul_f32_e32 v0, 0x4f7ffffe, v0
	v_cvt_u32_f32_e32 v0, v0
	s_nop 0
	v_readfirstlane_b32 s17, v0
	s_mul_i32 s16, s16, s17
	s_mul_hi_u32 s16, s17, s16
	s_add_i32 s17, s17, s16
	s_mul_hi_u32 s16, s10, s17
	s_mul_i32 s17, s16, s14
	s_sub_i32 s10, s10, s17
	s_add_i32 s24, s16, 1
	s_sub_i32 s17, s10, s14
	s_cmp_ge_u32 s10, s14
	s_cselect_b32 s16, s24, s16
	s_cselect_b32 s10, s17, s10
	s_add_i32 s17, s16, 1
	s_cmp_ge_u32 s10, s14
	s_cselect_b32 s10, s17, s16
	s_xor_b32 s10, s10, s15
	s_sub_i32 s10, s10, s15
	s_mul_i32 s13, s10, s13
	s_sub_i32 s11, s11, s13
	s_add_i32 s12, s11, s12

.LBB0_776:
	s_add_i32 s39, s39, 1
	s_mul_i32 s4, s39, s73
	s_mul_hi_u32 s5, s39, s72
	s_add_i32 s5, s5, s4
	s_mul_i32 s4, s39, s72
	s_add_u32 s4, s4, s2
	s_addc_u32 s5, s5, s3
	v_cmp_gt_i64_e32 vcc, s[4:5], v[142:143]
	v_cmp_lt_i64_e64 s[6:7], s[4:5], v[140:141]
	s_cbranch_vccnz .LBB0_782
	s_cmp_eq_u32 s66, 0x100
	s_cbranch_scc0 .Ltix_orig_3
	s_lshr_b32 s98, s4, 3
	s_and_b32 s99, s4, 7
	s_lshl_b32 s99, s99, 4
	s_and_b32 s41, s98, 7
	s_add_i32 s41, s41, s99
	s_cmp_ge_u32 s98, 32
	s_cselect_b32 s99, 8, 0
	s_cselect_b32 s40, 32, 0
	s_add_i32 s41, s41, s99
	s_sub_i32 s40, s98, s40
	s_lshr_b32 s40, s40, 3
	s_branch .LBB0_782
.Ltix_orig_3:
	s_ashr_i32 s5, s4, 31
	s_lshr_b32 s5, s5, 29
	s_add_i32 s16, s4, s5
	s_and_b32 s5, s16, -8
	s_sub_i32 s17, s4, s5
	s_cmp_gt_i32 s17, -1
	s_mov_b64 s[4:5], -1
	s_cbranch_scc0 .LBB0_779
	s_lshl_b32 s22, s17, 6
	s_mov_b64 s[4:5], 0

.LBB0_874:
	s_add_i32 s52, s9, 1
	s_mul_i32 s6, s52, s73
	s_mul_hi_u32 s7, s52, s72
	s_add_i32 s7, s7, s6
	s_mul_i32 s6, s52, s72
	s_add_u32 s24, s6, s2
	s_addc_u32 s25, s7, s3
	v_cmp_gt_i64_e32 vcc, s[24:25], v[142:143]
	v_cmp_lt_i64_e64 s[6:7], s[24:25], v[140:141]
	s_cbranch_vccnz .LBB0_876
	s_cmp_eq_u32 s66, 0x100
	s_cbranch_scc0 .Ltix_orig_4
	s_lshr_b32 s98, s24, 3
	s_and_b32 s99, s24, 7
	s_lshl_b32 s99, s99, 4
	s_and_b32 s22, s98, 7
	s_add_i32 s22, s22, s99
	s_cmp_ge_u32 s98, 80
	s_cselect_b32 s99, 8, 0
	s_cselect_b32 s20, 80, 0
	s_add_i32 s22, s22, s99
	s_sub_i32 s20, s98, s20
	s_lshr_b32 s20, s20, 3
	s_branch .LBB0_876
.Ltix_orig_4:
	s_ashr_i32 s11, s24, 31
	s_lshr_b32 s11, s11, 29
	s_add_i32 s11, s24, s11
	s_ashr_i32 s20, s11, 3
	s_and_b32 s11, s11, -8
	s_sub_i32 s11, s24, s11
	s_cmp_lt_i32 s11, 0
	s_cselect_b32 s21, s46, 0xa0
	s_mul_i32 s11, s21, s11
	s_add_i32 s11, s11, s20
	s_mul_hi_i32 s20, s11, 0x66666667
	s_lshr_b32 s21, s20, 31
	s_ashr_i32 s20, s20, 5
	s_add_i32 s20, s20, s21
	s_lshl_b32 s21, s20, 3
	s_sub_i32 s22, 0x80, s21
	s_min_i32 s22, s22, 8
	s_abs_i32 s23, s22
	v_cvt_f32_u32_e32 v0, s23
	s_sub_i32 s25, 0, s23
	s_mulk_i32 s20, 0x50
	s_sub_i32 s11, s11, s20
	v_rcp_iflag_f32_e32 v0, v0
	s_abs_i32 s20, s11
	s_xor_b32 s24, s11, s22
	s_ashr_i32 s24, s24, 31
	v_mul_f32_e32 v0, 0x4f7ffffe, v0
	v_cvt_u32_f32_e32 v0, v0
	s_nop 0
	v_readfirstlane_b32 s26, v0
	s_mul_i32 s25, s25, s26
	s_mul_hi_u32 s25, s26, s25
	s_add_i32 s26, s26, s25
	s_mul_hi_u32 s25, s20, s26
	s_mul_i32 s26, s25, s23
	s_sub_i32 s20, s20, s26
	s_add_i32 s27, s25, 1
	s_sub_i32 s26, s20, s23
	s_cmp_ge_u32 s20, s23
	s_cselect_b32 s25, s27, s25
	s_cselect_b32 s20, s26, s20
	s_add_i32 s26, s25, 1
	s_cmp_ge_u32 s20, s23
	s_cselect_b32 s20, s26, s25
	s_xor_b32 s20, s20, s24
	s_sub_i32 s20, s20, s24
	s_mul_i32 s22, s20, s22
	s_sub_i32 s11, s11, s22
	s_add_i32 s22, s11, s21
